# k45: k44 + attention gate rows requested as the last prologue loads into spare registers, kept in flight through the first pass of the tile loop (flag-selected wait counts), copied in the epilogue
# baseline (speedup 1.0000x reference)
; __device__ __forceinline__ float lane0(float v) { return __builtin_bit_cast(float, __builtin_amdgcn_readfirstlane(__builtin_bit_cast(int, v))); }
; #define ATT_GLD16(dst, ptr) asm volatile("global_load_dwordx4 %0, %1, off" : "=&v"(dst) : "v"(ptr) : "memory")
; __device__ __forceinline__ void attn_unit(const UnitDesc& u, LAS unsigned char* shm, float qkmax, float thresh) {
;     ...
;     { const int t2 = NT >= 2 ? NT - 2 : 0, t3 = NT >= 3 ? NT - 3 : 0, t4 = NT >= 4 ? NT - 4 : 0;
;       ATT_GLD16(kA, ksrc + (size_t)t2 * 64 * 512); ATT_GLD16(vA, vsrc + (size_t)t2 * 64 * 512);
;       ATT_GLD16(kB, ksrc + (size_t)t3 * 64 * 512); ATT_GLD16(vB, vsrc + (size_t)t3 * 64 * 512);
;       ATT_GLD16(kC, ksrc + (size_t)t4 * 64 * 512); ATT_GLD16(vC, vsrc + (size_t)t4 * 64 * 512); }
;     bf16x8 qr[4];
; #pragma unroll
;     for (int d0 = 0; d0 < 4; ++d0) qr[d0] = (bf16x8){0, 0, 0, 0, 0, 0, 0, 0};
;     if (active) { const bf16_t* Qw = u.Q + (size_t)(wid * 32 + r32) * 512;
; #pragma unroll
;         for (int d0 = 0; d0 < 4; ++d0) qr[d0] = *(const bf16x8*)(Qw + d0 * 16 + hi * 8); }
;     float carry = 0.f, Rown = 0.f, Rq0 = 0.f, inc4[4];
; #pragma unroll
;     for (int i = 0; i < 4; ++i) inc4[i] = suffix_incl(lfb[i], lane);
; #pragma unroll
;     for (int i = 0; i < 4; ++i) { if (i < nband) { const int jb = nband - 1 - i; const float R = carry + inc4[i] - lfb[i];
;         const float ro = __shfl(R, 32 * (wid & 1) + r32); if (jb == (wid >> 1)) Rown = ro;
;         if (jb == 0) Rq0 = __shfl(R, 0);
;         carry += lane0(inc4[i]); } }
;     ...
;         u32x4 zv4[4];
; #pragma unroll
;         for (int i = 0; i < 4; ++i) zv4[i] = *(const u32x4*)(u.Zg + (size_t)(wid * 32 + i * 8 + (lane >> 3)) * 512 + (lane & 7) * 8);
.LBB0_734:
	s_lshl_b64 s[12:13], s[28:29], 16
	v_lshl_add_u64 v[188:189], v[106:107], 0, s[12:13]
	global_load_dwordx4 v[66:69], v[188:189], off
	v_lshl_add_u64 v[188:189], v[108:109], 0, s[12:13]
	global_load_dwordx4 v[74:77], v[188:189], off
	s_lshl_b64 s[8:9], s[8:9], 16
	v_lshl_add_u64 v[188:189], v[106:107], 0, s[8:9]
	global_load_dwordx4 v[70:73], v[188:189], off
	v_lshl_add_u64 v[188:189], v[108:109], 0, s[8:9]
	global_load_dwordx4 v[82:85], v[188:189], off
	s_lshl_b64 s[8:9], s[10:11], 16
	v_lshl_add_u64 v[188:189], v[106:107], 0, s[8:9]
	global_load_dwordx4 v[78:81], v[188:189], off
	v_lshl_add_u64 v[188:189], v[108:109], 0, s[8:9]
	global_load_dwordx4 v[86:89], v[188:189], off
	s_lshl_b64 s[82:83], s[44:45], 1
	s_add_u32 s82, s24, s82
	s_addc_u32 s83, s25, s83
	s_lshl_b64 s[100:101], s[46:47], 1
	s_add_u32 s82, s82, s100
	s_addc_u32 s83, s83, s101
	v_lshrrev_b32_e32 v191, 3, v137
	v_or_b32_e32 v191, s49, v191
	v_and_b32_e32 v192, 56, v138
	v_lshlrev_b32_e32 v192, 1, v192
	v_lshl_add_u32 v191, v191, 10, v192
	v_add_u32_e32 v192, 0x2000, v191
	v_add_u32_e32 v193, 0x4000, v191
	v_add_u32_e32 v194, 0x6000, v191
	s_mov_b32 s81, 0
	global_load_dwordx4 v[198:201], v191, s[82:83]
	global_load_dwordx4 v[204:207], v192, s[82:83]
	global_load_dwordx4 v[234:237], v193, s[82:83]
	global_load_dwordx4 v[248:251], v194, s[82:83]
	v_lshrrev_b32_e32 v0, 4, v137
	v_cmp_ne_u32_e64 s[8:9], 1, v0
	v_cmp_eq_u32_e64 s[10:11], 2, v0
	s_waitcnt vmcnt(19)
	v_add_f32_dpp v0, v14, v14 row_shl:1 row_mask:0xf bank_mask:0xf bound_ctrl:1
	v_cmp_lt_u32_e64 s[6:7], 15, v137
	s_nop 0
	v_add_f32_dpp v0, v0, v0 row_shl:2 row_mask:0xf bank_mask:0xf bound_ctrl:1
	s_nop 1
	v_add_f32_dpp v0, v0, v0 row_shl:4 row_mask:0xf bank_mask:0xf bound_ctrl:1
	s_nop 1
	v_add_f32_dpp v0, v0, v0 row_shl:8 row_mask:0xf bank_mask:0xf bound_ctrl:1
	s_nop 0
	v_readlane_b32 s28, v0, 16
	v_readlane_b32 s70, v0, 32
	v_readlane_b32 s69, v0, 48
	s_and_saveexec_b64 s[12:13], s[6:7]
	s_xor_b64 s[12:13], exec, s[12:13]
	s_cbranch_execz .LBB0_740
	s_and_saveexec_b64 s[64:65], s[8:9]
	s_xor_b64 s[64:65], exec, s[64:65]
	v_mov_b32_e32 v11, s69
	v_cndmask_b32_e64 v11, 0, v11, s[10:11]
	s_andn2_saveexec_b64 s[64:65], s[64:65]
	v_mov_b32_e32 v11, s69
	v_add_f32_e32 v11, s70, v11
	s_or_b64 exec, exec, s[64:65]
.LBB0_740:
	s_andn2_saveexec_b64 s[12:13], s[12:13]
	v_mov_b32_e32 v11, s70
	v_add_f32_e32 v11, s28, v11
	v_add_f32_e32 v11, s69, v11
	s_or_b64 exec, exec, s[12:13]
	s_waitcnt vmcnt(18)
	v_add_f32_dpp v15, v140, v140 row_shl:1 row_mask:0xf bank_mask:0xf bound_ctrl:1
	s_nop 1
	v_add_f32_dpp v15, v15, v15 row_shl:2 row_mask:0xf bank_mask:0xf bound_ctrl:1
	s_nop 1
	v_add_f32_dpp v15, v15, v15 row_shl:4 row_mask:0xf bank_mask:0xf bound_ctrl:1
	s_nop 1
	v_add_f32_dpp v15, v15, v15 row_shl:8 row_mask:0xf bank_mask:0xf bound_ctrl:1
	s_nop 0
	v_readlane_b32 s28, v15, 16
	v_readlane_b32 s70, v15, 32
	v_readlane_b32 s69, v15, 48
	s_and_saveexec_b64 s[12:13], s[6:7]
	s_xor_b64 s[12:13], exec, s[12:13]
	s_cbranch_execz .LBB0_748
	s_and_saveexec_b64 s[64:65], s[8:9]
	s_xor_b64 s[64:65], exec, s[64:65]
	v_mov_b32_e32 v16, s69
	v_cndmask_b32_e64 v16, 0, v16, s[10:11]
	s_andn2_saveexec_b64 s[64:65], s[64:65]
	v_mov_b32_e32 v16, s69
	v_add_f32_e32 v16, s70, v16
	s_or_b64 exec, exec, s[64:65]
.LBB0_748:
	s_andn2_saveexec_b64 s[12:13], s[12:13]
	v_mov_b32_e32 v16, s70
	v_add_f32_e32 v16, s28, v16
	v_add_f32_e32 v16, s69, v16
	s_or_b64 exec, exec, s[12:13]
	s_waitcnt vmcnt(17)
	v_add_f32_dpp v17, v141, v141 row_shl:1 row_mask:0xf bank_mask:0xf bound_ctrl:1
	s_nop 1
	v_add_f32_dpp v17, v17, v17 row_shl:2 row_mask:0xf bank_mask:0xf bound_ctrl:1
	s_nop 1
	v_add_f32_dpp v17, v17, v17 row_shl:4 row_mask:0xf bank_mask:0xf bound_ctrl:1
	s_nop 1
	v_add_f32_dpp v17, v17, v17 row_shl:8 row_mask:0xf bank_mask:0xf bound_ctrl:1
	s_nop 0
	v_readlane_b32 s28, v17, 16
	v_readlane_b32 s70, v17, 32
	v_readlane_b32 s69, v17, 48
	s_and_saveexec_b64 s[12:13], s[6:7]
	s_xor_b64 s[12:13], exec, s[12:13]
	s_cbranch_execz .LBB0_756
	s_and_saveexec_b64 s[64:65], s[8:9]
	s_xor_b64 s[64:65], exec, s[64:65]
	v_mov_b32_e32 v18, s69
	v_cndmask_b32_e64 v18, 0, v18, s[10:11]
	s_andn2_saveexec_b64 s[64:65], s[64:65]
	v_mov_b32_e32 v18, s69
	v_add_f32_e32 v18, s70, v18
	s_or_b64 exec, exec, s[64:65]
.LBB0_756:
	s_andn2_saveexec_b64 s[12:13], s[12:13]
	v_mov_b32_e32 v18, s70
	v_add_f32_e32 v18, s28, v18
	v_add_f32_e32 v18, s69, v18
	s_or_b64 exec, exec, s[12:13]
	s_waitcnt vmcnt(16)
	v_add_f32_dpp v19, v139, v139 row_shl:1 row_mask:0xf bank_mask:0xf bound_ctrl:1
	s_nop 1
	v_add_f32_dpp v19, v19, v19 row_shl:2 row_mask:0xf bank_mask:0xf bound_ctrl:1
	s_nop 1
	v_add_f32_dpp v19, v19, v19 row_shl:4 row_mask:0xf bank_mask:0xf bound_ctrl:1
	s_nop 1
	v_add_f32_dpp v19, v19, v19 row_shl:8 row_mask:0xf bank_mask:0xf bound_ctrl:1
	s_nop 0
	v_readlane_b32 s28, v19, 16
	v_readlane_b32 s70, v19, 32
	v_readlane_b32 s69, v19, 48
	s_and_saveexec_b64 s[12:13], s[6:7]
	s_xor_b64 s[12:13], exec, s[12:13]
	s_cbranch_execz .LBB0_764
	s_and_saveexec_b64 s[64:65], s[8:9]
	s_xor_b64 s[64:65], exec, s[64:65]
	v_mov_b32_e32 v20, s69
	v_cndmask_b32_e64 v20, 0, v20, s[10:11]
	s_andn2_saveexec_b64 s[64:65], s[64:65]
	v_mov_b32_e32 v20, s69
	v_add_f32_e32 v20, s70, v20
	s_or_b64 exec, exec, s[64:65]

; #define LAS __attribute__((address_space(3)))
; __device__ __forceinline__ float lane0(float v) { return __builtin_bit_cast(float, __builtin_amdgcn_readfirstlane(__builtin_bit_cast(int, v))); }
; __device__ __forceinline__ void attn_unit(const UnitDesc& u, LAS unsigned char* shm, float qkmax, float thresh) {
;     ...
;     const float ci = -Rown * LOG2E - qkmax;
;     const float kbq0 = Rq0 * LOG2E;
;     const int qabs = u.q0 + wid * 32 + r32;
;     float l_reg = 0.f; f32x16 o[2]; o[0] = f32x16{}; o[1] = f32x16{};
;     float lA = lfb[1], lB = lfb[2], lC = lfb[3];
;     { const float lf = lfb[0]; const float inc = inc4[0]; wsf[lane] = (inc - lf) * LOG2E; carry = lane0(inc);
;       *(LAS u32x4*)kdst = kreg; *(LAS u32x4*)vdst = vreg;
;       asm volatile("" : "+v"(qr[0]), "+v"(qr[1]), "+v"(qr[2]), "+v"(qr[3]));
;       asm volatile("s_waitcnt vmcnt(0)" : "+v"(kA), "+v"(vA), "+v"(kB), "+v"(vB), "+v"(kC), "+v"(vC) :: "memory"); }
;     int slot = 0, tile = NT - 1; bool stop = false;
.LBB0_772:
	v_lshlrev_b32_e32 v15, 1, v12
	s_lshl_b32 s12, s52, 10
	v_and_b32_e32 v15, 32, v15
	s_add_i32 s13, 0, 0x2000
	v_lshlrev_b32_e32 v142, 2, v136
	v_lshrrev_b32_e32 v12, 2, v12
	s_add_i32 s12, s12, 0
	v_add_u32_e32 v15, s13, v15
	v_and_or_b32 v12, v12, 3, v142
	s_lshl_b32 s13, s52, 9
	v_lshlrev_b32_e32 v12, 6, v12
	s_sub_i32 s53, s12, s13
	v_add_u32_e32 v147, s66, v10
	v_sub_f32_e32 v10, v0, v14
	v_lshl_add_u32 v143, v137, 4, s12
	v_add3_u32 v144, v15, v13, v12
	s_mov_b32 s12, 0xbfb8aa3b
	s_waitcnt lgkmcnt(0)
	v_mul_f32_e32 v146, 0x3fb8aa3b, v11
	v_mul_f32_e32 v10, 0x3fb8aa3b, v10
	v_lshl_add_u32 v11, v137, 2, s53
	v_mov_b32_e32 v14, v1
	v_mov_b32_e32 v15, v1
	v_lshlrev_b32_e32 v16, 10, v136
	v_lshlrev_b32_e32 v17, 4, v135
	v_fma_f32 v112, v21, s12, -v130
	v_mul_f32_e32 v197, 0x3fb8aa3b, v21
	s_mov_b64 s[98:99], 0
	s_nop 0
	v_readfirstlane_b32 s100, v197
	s_nop 3
	v_mov_b32_e32 v197, s100
	ds_write_b32 v11, v10 offset:32768
	v_readfirstlane_b32 s12, v0
	s_waitcnt vmcnt(14)
	ds_write_b128 v143, v[2:5]
	ds_write_b128 v143, v[6:9] offset:8192
	v_mov_b32_e32 v0, v1
	v_mov_b32_e32 v2, v1
	v_mov_b32_e32 v3, v1
	v_mov_b32_e32 v4, v1
	v_mov_b32_e32 v5, v1
	v_mov_b32_e32 v6, v1
	v_mov_b32_e32 v7, v1
	v_mov_b32_e32 v8, v1
	v_mov_b32_e32 v9, v1
	v_mov_b32_e32 v10, v1
	v_mov_b32_e32 v11, v1
	v_mov_b32_e32 v12, v1
	v_mov_b32_e32 v13, v1
	v_mov_b64_e32 v[48:49], v[14:15]
	v_mov_b64_e32 v[64:65], v[14:15]
	v_mov_b64_e32 v[32:33], v[14:15]
	v_add3_u32 v145, 0, v16, v17
	s_add_i32 s73, s66, s49
	v_mov_b64_e32 v[46:47], v[12:13]
	v_mov_b64_e32 v[44:45], v[10:11]
	v_mov_b64_e32 v[42:43], v[8:9]
	v_mov_b64_e32 v[40:41], v[6:7]
	v_mov_b64_e32 v[38:39], v[4:5]
	v_mov_b64_e32 v[36:37], v[2:3]
	v_mov_b64_e32 v[34:35], v[0:1]
	v_mov_b64_e32 v[62:63], v[12:13]
	v_mov_b64_e32 v[60:61], v[10:11]
	v_mov_b64_e32 v[58:59], v[8:9]
	v_mov_b64_e32 v[56:57], v[6:7]
	v_mov_b64_e32 v[54:55], v[4:5]
	v_mov_b64_e32 v[52:53], v[2:3]
	v_mov_b64_e32 v[50:51], v[0:1]
	v_mov_b64_e32 v[30:31], v[12:13]
	v_mov_b64_e32 v[28:29], v[10:11]
	v_mov_b64_e32 v[26:27], v[8:9]
	v_mov_b64_e32 v[24:25], v[6:7]
	v_mov_b64_e32 v[22:23], v[4:5]
	v_mov_b64_e32 v[20:21], v[2:3]
	v_mov_b64_e32 v[18:19], v[0:1]
	v_mov_b64_e32 v[16:17], v[14:15]
	s_sub_i32 s72, s67, s28
	s_add_i32 s73, s73, 31
	v_mov_b32_e32 v113, v112
	v_mov_b32_e32 v114, v112
	v_mov_b32_e32 v115, v112
	v_mov_b32_e32 v116, v112
	v_mov_b32_e32 v117, v112
	v_mov_b32_e32 v118, v112
	v_mov_b32_e32 v119, v112
	v_mov_b32_e32 v120, v112
	v_mov_b32_e32 v121, v112
	v_mov_b32_e32 v122, v112
	v_mov_b32_e32 v123, v112
	v_mov_b32_e32 v124, v112
	v_mov_b32_e32 v125, v112
	v_mov_b32_e32 v126, v112
	v_mov_b32_e32 v127, v112
	s_lshl_b32 s75, s67, 6
	s_mov_b32 s70, 0
	v_mov_b32_e32 v148, 0
	s_mov_b64 s[62:63], 0
	v_mov_b32_e32 v150, s12
	v_mov_b64_e32 v[14:15], v[12:13]
	v_mov_b64_e32 v[12:13], v[10:11]
	v_mov_b64_e32 v[10:11], v[8:9]
	v_mov_b64_e32 v[8:9], v[6:7]
	v_mov_b64_e32 v[6:7], v[4:5]
	v_mov_b64_e32 v[4:5], v[2:3]
	v_mov_b64_e32 v[2:3], v[0:1]
	s_waitcnt vmcnt(10)
	s_branch .LBB0_777

; #define LAS __attribute__((address_space(3)))
; template <bool BAND>
; __device__ __forceinline__ void tile_body(f32x16* o, float& l_reg, const bf16x8* qr, const LAS unsigned char* kbs, const LAS float* wb, int vb, float ci, int hi, int keybase, int qabs) {
;     f32x16 p0, p1;
; #pragma unroll
;     for (int g4 = 0; g4 < 4; ++g4) {
;         const f32x4 ba = *(const LAS f32x4*)(wb + 8 * g4 + 4 * hi) + ci, bb = *(const LAS f32x4*)(wb + 32 + 8 * g4 + 4 * hi) + ci;
; #pragma unroll
;         for (int e = 0; e < 4; ++e) { p0[4 * g4 + e] = ba[e]; p1[4 * g4 + e] = bb[e]; }
;     }
; #pragma unroll
;     for (int d0 = 0; d0 < 4; ++d0) {
;         const bf16x8 b0 = *(const LAS bf16x8*)(kbs + d0 * 2048), b1 = *(const LAS bf16x8*)(kbs + d0 * 2048 + 512);
;         p0 = __builtin_amdgcn_mfma_f32_32x32x16_bf16(b0, qr[d0], p0, 0, 0, 0); p1 = __builtin_amdgcn_mfma_f32_32x32x16_bf16(b1, qr[d0], p1, 0, 0, 0); }
.LBB0_783:
	s_andn2_saveexec_b64 s[12:13], s[12:13]
	v_mov_b32_e32 v149, s67
	v_add_f32_e32 v149, s28, v149
	v_add_f32_e32 v149, s66, v149
	s_or_b64 exec, exec, s[12:13]
	v_add_f32_e32 v149, v0, v149
	s_xor_b32 s74, s70, 1
	v_add_f32_e32 v0, v150, v149
	s_lshl_b32 s12, s74, 8
	v_sub_f32_e32 v0, v0, v140
	s_add_i32 s71, s53, s12
	s_lshl_b32 s78, s74, 14
	s_max_i32 s12, s48, 4
	v_mul_f32_e32 v140, 0x3fb8aa3b, v0
	v_lshl_add_u32 v0, v137, 2, s71
	v_readfirstlane_b32 s76, v149
	v_add_u32_e32 v149, s78, v143
	s_add_i32 s28, s12, -4
	ds_write_b32 v0, v140 offset:32768
	s_cmp_lg_u32 s81, 0
	s_cbranch_scc1 .Lmy_zw0_s
	s_waitcnt vmcnt(8)
	s_branch .Lmy_zw0_j
.Lmy_zw0_s:
	s_waitcnt vmcnt(4)
.Lmy_zw0_j:
	ds_write_b128 v149, v[66:69]
	ds_write_b128 v149, v[74:77] offset:8192
	s_lshl_b64 s[12:13], s[28:29], 11
	s_waitcnt lgkmcnt(0)
	v_lshl_add_u64 v[66:67], v[110:111], 0, s[12:13]
	s_lshl_b64 s[12:13], s[28:29], 16
	global_load_dword v140, v[66:67], off
	v_lshl_add_u64 v[74:75], v[106:107], 0, s[12:13]
	global_load_dwordx4 v[66:69], v[74:75], off
	v_cndmask_b32_e64 v74, 0, 1, s[58:59]
	v_lshl_add_u64 v[152:153], v[108:109], 0, s[12:13]
	v_cmp_ne_u32_e64 s[12:13], 1, v74
	global_load_dwordx4 v[74:77], v[152:153], off
	s_andn2_b64 vcc, exec, s[58:59]
	s_cbranch_vccnz .LBB0_792
	s_and_b64 vcc, exec, s[98:99]
	s_cbranch_vccnz .LBB0_792
	s_sub_i32 s28, s75, 64
	s_cmp_gt_i32 s28, s73
	s_cbranch_scc1 .LBB0_792
	s_lshl_b32 s64, s70, 8
	s_lshl_b32 s28, s70, 14
	s_add_i32 s66, s53, s64
	s_cmp_lt_i32 s48, s72
	v_add_u32_e32 v151, s28, v144
	s_mov_b64 s[64:65], -1
	v_add_u32_e32 v152, s28, v145
	v_lshl_add_u32 v153, v142, 2, s66
	s_cbranch_scc1 .LBB0_789
	ds_read_b128 v[34:37], v153 offset:32768
	ds_read_b128 v[38:41], v153 offset:32800
	ds_read_b128 v[42:45], v153 offset:32832
	ds_read_b128 v[46:49], v153 offset:32864
	ds_read_b128 v[50:53], v153 offset:32896
	ds_read_b128 v[54:57], v153 offset:32928
	ds_read_b128 v[58:61], v153 offset:32960
	ds_read_b128 v[62:65], v153 offset:32992
	ds_read_b128 v[154:157], v152
	ds_read_b128 v[158:161], v152 offset:512
	s_waitcnt lgkmcnt(4)
	ds_read_b128 v[210:213], v152 offset:2048
	ds_read_b128 v[214:217], v152 offset:2560
	ds_read_b128 v[218:221], v152 offset:4096
	ds_read_b128 v[222:225], v152 offset:4608
	ds_read_b128 v[226:229], v152 offset:6656
	ds_read_b128 v[230:233], v152 offset:6144
	v_pk_add_f32 v[56:57], v[118:119], v[56:57]
	s_waitcnt lgkmcnt(9)
	v_pk_add_f32 v[60:61], v[122:123], v[60:61]
	s_waitcnt lgkmcnt(8)
	v_pk_add_f32 v[64:65], v[126:127], v[64:65]
	v_pk_add_f32 v[52:53], v[114:115], v[52:53]
	v_pk_add_f32 v[62:63], v[124:125], v[62:63]
	v_pk_add_f32 v[58:59], v[120:121], v[58:59]
	v_pk_add_f32 v[54:55], v[116:117], v[54:55]
	v_pk_add_f32 v[50:51], v[112:113], v[50:51]
	v_pk_add_f32 v[48:49], v[126:127], v[48:49]
	v_pk_add_f32 v[44:45], v[122:123], v[44:45]
	v_pk_add_f32 v[40:41], v[118:119], v[40:41]
	v_pk_add_f32 v[36:37], v[114:115], v[36:37]
	v_pk_add_f32 v[46:47], v[124:125], v[46:47]
	v_pk_add_f32 v[42:43], v[120:121], v[42:43]
	v_pk_add_f32 v[38:39], v[116:117], v[38:39]
	v_pk_add_f32 v[34:35], v[112:113], v[34:35]
	s_waitcnt lgkmcnt(6)
	v_mfma_f32_32x32x16_bf16 v[50:65], v[158:161], v[94:97], v[50:65]
	v_mfma_f32_32x32x16_bf16 v[34:49], v[154:157], v[94:97], v[34:49]
	s_waitcnt lgkmcnt(4)
	v_mfma_f32_32x32x16_bf16 v[50:65], v[214:217], v[98:101], v[50:65]
	v_mfma_f32_32x32x16_bf16 v[34:49], v[210:213], v[98:101], v[34:49]
	s_waitcnt lgkmcnt(2)
	v_mfma_f32_32x32x16_bf16 v[50:65], v[222:225], v[102:105], v[50:65]
	v_mfma_f32_32x32x16_bf16 v[34:49], v[218:221], v[102:105], v[34:49]
	s_waitcnt lgkmcnt(1)
	v_mfma_f32_32x32x16_bf16 v[50:65], v[226:229], v[90:93], v[50:65]
	v_add_u32_e32 v154, s75, v142
	v_subrev_u32_e32 v156, 32, v154
	v_subrev_u32_e32 v155, 64, v154
	v_cmp_le_i32_e32 vcc, v156, v147
	s_waitcnt lgkmcnt(0)
; __device__ __forceinline__ void pv(f32x16* o, int vb, bf16x8 pa0, bf16x8 pa1, bf16x8 pa2, bf16x8 pa3) {
; #pragma unroll
;     for (int d0 = 0; d0 < 2; ++d0) { s16x4 lo[4], hi[4];
; #pragma unroll
;         for (int ks = 0; ks < 4; ++ks) {
;             asm volatile("ds_read_b64_tr_b16 %0,%1 offset:%c2" : "=&v"(lo[ks]) : "v"(vb), "i"(d0 * 4096 + ks * 1024) : "memory");
;             asm volatile("ds_read_b64_tr_b16 %0,%1 offset:%c2" : "=&v"(hi[ks]) : "v"(vb), "i"(d0 * 4096 + ks * 1024 + 512) : "memory"); }
;         asm volatile("s_waitcnt lgkmcnt(0)" ::: "memory"); __builtin_amdgcn_sched_barrier(0);
;     ...
;         o[d0] = __builtin_amdgcn_mfma_f32_32x32x16_bf16(pa0, PK(0), o[d0], 0, 0, 0);
;         o[d0] = __builtin_amdgcn_mfma_f32_32x32x16_bf16(pa1, PK(1), o[d0], 0, 0, 0);
;         o[d0] = __builtin_amdgcn_mfma_f32_32x32x16_bf16(pa2, PK(2), o[d0], 0, 0, 0);
;         o[d0] = __builtin_amdgcn_mfma_f32_32x32x16_bf16(pa3, PK(3), o[d0], 0, 0, 0);
; template <bool BAND>
; __device__ __forceinline__ void tile_body(f32x16* o, float& l_reg, const bf16x8* qr, const LAS unsigned char* kbs, const LAS float* wb, int vb, float ci, int hi, int keybase, int qabs) {
;     ...
;     if (BAND) {
; #pragma unroll
;         for (int r = 0; r < 16; ++r) { const int key = keybase + 8 * (r >> 2) + (r & 3); if (key > qabs) p0[r] = -INFINITY; if (key + 32 > qabs) p1[r] = -INFINITY; }
;     }
;     f32x2 s2 = {0.f, 0.f};
; #pragma unroll
;     for (int r = 0; r < 16; r += 2) {
;         p0[r] = __builtin_amdgcn_exp2f(p0[r]); p0[r + 1] = __builtin_amdgcn_exp2f(p0[r + 1]); p1[r] = __builtin_amdgcn_exp2f(p1[r]); p1[r + 1] = __builtin_amdgcn_exp2f(p1[r + 1]);
;         s2 += (f32x2){p0[r], p0[r + 1]}; s2 += (f32x2){p1[r], p1[r + 1]}; }
;     l_reg += s2.x + s2.y;
;     u32x4 pw0, pw1, pw2, pw3;
;     pw0 = (u32x4){cvtpk(p0[0], p0[1]), cvtpk(p0[2], p0[3]), cvtpk(p0[4], p0[5]), cvtpk(p0[6], p0[7])};
;     pw1 = (u32x4){cvtpk(p0[8], p0[9]), cvtpk(p0[10], p0[11]), cvtpk(p0[12], p0[13]), cvtpk(p0[14], p0[15])};
;     pw2 = (u32x4){cvtpk(p1[0], p1[1]), cvtpk(p1[2], p1[3]), cvtpk(p1[4], p1[5]), cvtpk(p1[6], p1[7])};
;     pw3 = (u32x4){cvtpk(p1[8], p1[9]), cvtpk(p1[10], p1[11]), cvtpk(p1[12], p1[13]), cvtpk(p1[14], p1[15])};
;     pv(o, vb, __builtin_bit_cast(bf16x8, pw0), __builtin_bit_cast(bf16x8, pw1), __builtin_bit_cast(bf16x8, pw2), __builtin_bit_cast(bf16x8, pw3));
	v_mfma_f32_32x32x16_bf16 v[34:49], v[230:233], v[90:93], v[34:49]
	s_nop 5
	v_cndmask_b32_e32 v50, v134, v50, vcc
	v_cmp_lt_i32_e32 vcc, v155, v147
	s_nop 3
	v_cndmask_b32_e32 v35, v134, v35, vcc
	v_cmp_le_i32_e32 vcc, v155, v147
	v_subrev_u32_e32 v155, 31, v154
	v_exp_f32_e32 v35, v35
	v_cndmask_b32_e32 v34, v134, v34, vcc
	v_cmp_le_i32_e32 vcc, v155, v147
	v_subrev_u32_e32 v155, 62, v154
	v_exp_f32_e32 v34, v34
	v_cndmask_b32_e32 v51, v134, v51, vcc
	v_cmp_le_i32_e32 vcc, v155, v147
	s_nop 1
	v_cndmask_b32_e32 v155, v134, v36, vcc
	v_subrev_u32_e32 v36, 30, v154
	v_cmp_le_i32_e32 vcc, v36, v147
	v_subrev_u32_e32 v36, 61, v154
	s_nop 0
	v_cndmask_b32_e32 v52, v134, v52, vcc
	v_cmp_le_i32_e32 vcc, v36, v147
	v_subrev_u32_e32 v36, 29, v154
	s_nop 0
	v_cndmask_b32_e32 v156, v134, v37, vcc
	v_cmp_le_i32_e32 vcc, v36, v147
	v_subrev_u32_e32 v36, 56, v154
	v_exp_f32_e32 v37, v51
	v_cndmask_b32_e32 v53, v134, v53, vcc
	v_cmp_le_i32_e32 vcc, v36, v147
	v_subrev_u32_e32 v36, 24, v154
	s_nop 0
	v_cndmask_b32_e32 v157, v134, v38, vcc
	v_cmp_le_i32_e32 vcc, v36, v147
	v_subrev_u32_e32 v36, 55, v154
	v_exp_f32_e32 v38, v155
	v_cndmask_b32_e32 v54, v134, v54, vcc
	v_cmp_le_i32_e32 vcc, v36, v147
	v_subrev_u32_e32 v36, 23, v154
	s_nop 0
	v_cndmask_b32_e32 v158, v134, v39, vcc
	v_cmp_le_i32_e32 vcc, v36, v147
	v_subrev_u32_e32 v36, 54, v154
	v_exp_f32_e32 v39, v156
	v_cndmask_b32_e32 v55, v134, v55, vcc
	v_cmp_le_i32_e32 vcc, v36, v147
	v_subrev_u32_e32 v36, 22, v154
	v_cvt_pk_bf16_f32 v156, v34, v35
	v_cndmask_b32_e32 v159, v134, v40, vcc
	v_cmp_le_i32_e32 vcc, v36, v147
	v_subrev_u32_e32 v36, 53, v154
	v_exp_f32_e32 v40, v52
	v_cndmask_b32_e32 v56, v134, v56, vcc
	v_cmp_le_i32_e32 vcc, v36, v147
	v_subrev_u32_e32 v36, 21, v154
	s_nop 0
	v_cndmask_b32_e32 v160, v134, v41, vcc
	v_cmp_le_i32_e32 vcc, v36, v147
	v_subrev_u32_e32 v36, 48, v154
	v_exp_f32_e32 v41, v53
	v_cndmask_b32_e32 v57, v134, v57, vcc
	v_cmp_le_i32_e32 vcc, v36, v147
	v_add_u32_e32 v36, -16, v154
	v_exp_f32_e32 v51, v57
	v_cndmask_b32_e32 v161, v134, v42, vcc
	v_cmp_le_i32_e32 vcc, v36, v147
	v_subrev_u32_e32 v36, 47, v154
	v_exp_f32_e32 v52, v161
	v_cndmask_b32_e32 v58, v134, v58, vcc
	v_cmp_le_i32_e32 vcc, v36, v147
	v_add_u32_e32 v36, -15, v154
	s_nop 0
	v_cndmask_b32_e32 v162, v134, v43, vcc
	v_cmp_le_i32_e32 vcc, v36, v147
	v_subrev_u32_e32 v36, 46, v154
	v_pk_add_f32 v[42:43], v[34:35], 0 op_sel_hi:[1,0]
	v_cndmask_b32_e32 v59, v134, v59, vcc
	v_cmp_le_i32_e32 vcc, v36, v147
	v_add_u32_e32 v36, -14, v154
	v_exp_f32_e32 v53, v162
	v_cndmask_b32_e32 v163, v134, v44, vcc
	v_cmp_le_i32_e32 vcc, v36, v147
	v_subrev_u32_e32 v36, 45, v154
	v_exp_f32_e32 v44, v157
	v_cndmask_b32_e32 v60, v134, v60, vcc
	v_cmp_le_i32_e32 vcc, v36, v147
	v_add_u32_e32 v36, -13, v154
	v_cvt_pk_bf16_f32 v157, v38, v39
	v_cndmask_b32_e32 v164, v134, v45, vcc
	v_cmp_le_i32_e32 vcc, v36, v147
	v_subrev_u32_e32 v36, 40, v154
	v_exp_f32_e32 v45, v158
	v_cndmask_b32_e32 v61, v134, v61, vcc
	v_cmp_le_i32_e32 vcc, v36, v147
	v_add_u32_e32 v36, -8, v154
	v_exp_f32_e32 v57, v164
	v_cndmask_b32_e32 v165, v134, v46, vcc
	v_cmp_le_i32_e32 vcc, v36, v147
	v_subrev_u32_e32 v36, 39, v154
	v_exp_f32_e32 v46, v54
	v_cndmask_b32_e32 v62, v134, v62, vcc
	v_cmp_le_i32_e32 vcc, v36, v147
	v_add_u32_e32 v36, -7, v154
	v_exp_f32_e32 v54, v58
	v_cndmask_b32_e32 v166, v134, v47, vcc
	v_cmp_le_i32_e32 vcc, v36, v147
	v_subrev_u32_e32 v36, 38, v154
	v_exp_f32_e32 v47, v55
	v_cndmask_b32_e32 v63, v134, v63, vcc
	v_cmp_le_i32_e32 vcc, v36, v147
	v_add_u32_e32 v36, -6, v154
	v_exp_f32_e32 v55, v59
	v_cndmask_b32_e32 v167, v134, v48, vcc
	v_cmp_le_i32_e32 vcc, v36, v147
	v_subrev_u32_e32 v36, 37, v154
	v_exp_f32_e32 v48, v159
	v_cndmask_b32_e32 v168, v134, v64, vcc
	v_cmp_le_i32_e32 vcc, v36, v147
	v_add_u32_e32 v36, -5, v154
	v_exp_f32_e32 v58, v60
	v_cndmask_b32_e32 v169, v134, v49, vcc
	v_cmp_le_i32_e32 vcc, v36, v147
	v_exp_f32_e32 v36, v50
	v_exp_f32_e32 v49, v160
	v_exp_f32_e32 v50, v56
	v_exp_f32_e32 v56, v163
	v_pk_add_f32 v[42:43], v[36:37], v[42:43]
	v_exp_f32_e32 v59, v61
	v_pk_add_f32 v[42:43], v[38:39], v[42:43]
	v_exp_f32_e32 v64, v167
	v_pk_add_f32 v[42:43], v[40:41], v[42:43]
	v_cvt_pk_bf16_f32 v167, v50, v51
	v_pk_add_f32 v[42:43], v[44:45], v[42:43]
	v_exp_f32_e32 v60, v165
	v_pk_add_f32 v[42:43], v[46:47], v[42:43]
	v_exp_f32_e32 v61, v166
	v_pk_add_f32 v[42:43], v[48:49], v[42:43]
	v_cvt_pk_bf16_f32 v160, v52, v53
	v_pk_add_f32 v[42:43], v[50:51], v[42:43]
	ds_read_b64_tr_b16 v[50:51],v151 offset:0
	v_exp_f32_e32 v62, v62
	v_pk_add_f32 v[42:43], v[52:53], v[42:43]
	ds_read_b64_tr_b16 v[52:53],v151 offset:512
	v_exp_f32_e32 v63, v63
	v_pk_add_f32 v[42:43], v[54:55], v[42:43]
	v_exp_f32_e32 v172, v168
	v_cvt_pk_bf16_f32 v168, v54, v55
	ds_read_b64_tr_b16 v[54:55],v151 offset:1024
	v_cndmask_b32_e32 v154, v134, v65, vcc
	v_pk_add_f32 v[42:43], v[56:57], v[42:43]
	v_exp_f32_e32 v65, v169
	v_cvt_pk_bf16_f32 v161, v56, v57
	ds_read_b64_tr_b16 v[56:57],v151 offset:1536
	v_pk_add_f32 v[42:43], v[58:59], v[42:43]
	v_exp_f32_e32 v173, v154
	v_cvt_pk_bf16_f32 v169, v58, v59
	ds_read_b64_tr_b16 v[58:59],v151 offset:2048
	v_pk_add_f32 v[42:43], v[60:61], v[42:43]
	v_cvt_pk_bf16_f32 v162, v60, v61
	ds_read_b64_tr_b16 v[60:61],v151 offset:2560
	v_pk_add_f32 v[42:43], v[62:63], v[42:43]
	v_cvt_pk_bf16_f32 v170, v62, v63
	ds_read_b64_tr_b16 v[62:63],v151 offset:3072
	v_pk_add_f32 v[42:43], v[64:65], v[42:43]
	v_cvt_pk_bf16_f32 v163, v64, v65
	ds_read_b64_tr_b16 v[64:65],v151 offset:3584
	v_pk_add_f32 v[42:43], v[172:173], v[42:43]
	s_waitcnt lgkmcnt(0)
	v_cvt_pk_bf16_f32 v158, v44, v45
	v_add_f32_e32 v42, v42, v43
	v_add_f32_e32 v154, v148, v42
	v_cvt_pk_bf16_f32 v159, v48, v49
	v_cvt_pk_bf16_f32 v164, v36, v37
	v_cvt_pk_bf16_f32 v165, v40, v41
	v_cvt_pk_bf16_f32 v166, v46, v47
	v_cvt_pk_bf16_f32 v171, v172, v173
	v_mfma_f32_32x32x16_bf16 v[2:17], v[156:159], v[50:53], v[2:17]
	ds_read_b64_tr_b16 v[172:173],v151 offset:4096
	ds_read_b64_tr_b16 v[174:175],v151 offset:4608
	ds_read_b64_tr_b16 v[176:177],v151 offset:5120
	ds_read_b64_tr_b16 v[178:179],v151 offset:5632
	ds_read_b64_tr_b16 v[180:181],v151 offset:6144
	ds_read_b64_tr_b16 v[182:183],v151 offset:6656
	ds_read_b64_tr_b16 v[184:185],v151 offset:7168
	v_mfma_f32_32x32x16_bf16 v[2:17], v[160:163], v[54:57], v[2:17]
	ds_read_b64_tr_b16 v[186:187],v151 offset:7680
	s_waitcnt lgkmcnt(0)
	v_mfma_f32_32x32x16_bf16 v[2:17], v[164:167], v[58:61], v[2:17]
	v_mfma_f32_32x32x16_bf16 v[2:17], v[168:171], v[62:65], v[2:17]
	v_mfma_f32_32x32x16_bf16 v[18:33], v[156:159], v[172:175], v[18:33]
	s_mov_b64 s[64:65], 0
	v_mfma_f32_32x32x16_bf16 v[18:33], v[160:163], v[176:179], v[18:33]
	v_mfma_f32_32x32x16_bf16 v[18:33], v[164:167], v[180:183], v[18:33]
	v_mfma_f32_32x32x16_bf16 v[18:33], v[168:171], v[184:187], v[18:33]

.LBB0_799:
	s_andn2_saveexec_b64 s[66:67], s[66:67]
	v_mov_b32_e32 v151, s79
	v_add_f32_e32 v151, s28, v151
	v_add_f32_e32 v153, s77, v151
	s_or_b64 exec, exec, s[66:67]
	v_add_f32_e32 v151, s76, v150
	v_add_f32_e32 v150, v152, v153
	v_add_f32_e32 v152, v151, v150
	s_lshl_b32 s28, s70, 8
	v_sub_f32_e32 v141, v152, v141
	s_add_i32 s76, s53, s28
	v_mul_f32_e32 v141, 0x3fb8aa3b, v141
	v_lshl_add_u32 v152, v137, 2, s76
	s_lshl_b32 s77, s70, 14
	ds_write_b32 v152, v141 offset:32768
	v_add_u32_e32 v141, s77, v143
	s_max_i32 s28, s48, 5
	s_cmp_lg_u32 s81, 0
	s_cbranch_scc1 .Lmy_zw1_s
	s_waitcnt vmcnt(8)
	s_branch .Lmy_zw1_j

; #define LAS __attribute__((address_space(3)))
; __device__ __forceinline__ unsigned cvtpk(float lo, float hi) { typedef __bf16 bf16x2_t __attribute__((ext_vector_type(2))); f32x2 v = {lo, hi}; bf16x2_t b = __builtin_convertvector(v, bf16x2_t); return __builtin_bit_cast(unsigned, b); }
; template <bool BAND>
; __device__ __forceinline__ void tile_body(f32x16* o, float& l_reg, const bf16x8* qr, const LAS unsigned char* kbs, const LAS float* wb, int vb, float ci, int hi, int keybase, int qabs) {
;     f32x16 p0, p1;
; #pragma unroll
;     for (int g4 = 0; g4 < 4; ++g4) {
;         const f32x4 ba = *(const LAS f32x4*)(wb + 8 * g4 + 4 * hi) + ci, bb = *(const LAS f32x4*)(wb + 32 + 8 * g4 + 4 * hi) + ci;
; #pragma unroll
;         for (int e = 0; e < 4; ++e) { p0[4 * g4 + e] = ba[e]; p1[4 * g4 + e] = bb[e]; }
;     }
; #pragma unroll
;     for (int d0 = 0; d0 < 4; ++d0) {
;         const bf16x8 b0 = *(const LAS bf16x8*)(kbs + d0 * 2048), b1 = *(const LAS bf16x8*)(kbs + d0 * 2048 + 512);
;         p0 = __builtin_amdgcn_mfma_f32_32x32x16_bf16(b0, qr[d0], p0, 0, 0, 0); p1 = __builtin_amdgcn_mfma_f32_32x32x16_bf16(b1, qr[d0], p1, 0, 0, 0); }
;     if (BAND) {
; #pragma unroll
;         for (int r = 0; r < 16; ++r) { const int key = keybase + 8 * (r >> 2) + (r & 3); if (key > qabs) p0[r] = -INFINITY; if (key + 32 > qabs) p1[r] = -INFINITY; }
;     }
;     f32x2 s2 = {0.f, 0.f};
; #pragma unroll
;     for (int r = 0; r < 16; r += 2) {
;         p0[r] = __builtin_amdgcn_exp2f(p0[r]); p0[r + 1] = __builtin_amdgcn_exp2f(p0[r + 1]); p1[r] = __builtin_amdgcn_exp2f(p1[r]); p1[r + 1] = __builtin_amdgcn_exp2f(p1[r + 1]);
;         s2 += (f32x2){p0[r], p0[r + 1]}; s2 += (f32x2){p1[r], p1[r + 1]}; }
;     l_reg += s2.x + s2.y;
;     u32x4 pw0, pw1, pw2, pw3;
;     pw0 = (u32x4){cvtpk(p0[0], p0[1]), cvtpk(p0[2], p0[3]), cvtpk(p0[4], p0[5]), cvtpk(p0[6], p0[7])};
;     pw1 = (u32x4){cvtpk(p0[8], p0[9]), cvtpk(p0[10], p0[11]), cvtpk(p0[12], p0[13]), cvtpk(p0[14], p0[15])};
;     pw2 = (u32x4){cvtpk(p1[0], p1[1]), cvtpk(p1[2], p1[3]), cvtpk(p1[4], p1[5]), cvtpk(p1[6], p1[7])};
;     pw3 = (u32x4){cvtpk(p1[8], p1[9]), cvtpk(p1[10], p1[11]), cvtpk(p1[12], p1[13]), cvtpk(p1[14], p1[15])};
;     pv(o, vb, __builtin_bit_cast(bf16x8, pw0), __builtin_bit_cast(bf16x8, pw1), __builtin_bit_cast(bf16x8, pw2), __builtin_bit_cast(bf16x8, pw3));
; }
.Lmy_zw1_j:
	ds_write_b128 v141, v[70:73]
	ds_write_b128 v141, v[82:85] offset:8192
	s_add_i32 s28, s28, -5
	s_waitcnt lgkmcnt(0)
	s_lshl_b64 s[66:67], s[28:29], 11
	v_lshl_add_u64 v[70:71], v[110:111], 0, s[66:67]
	global_load_dword v141, v[70:71], off
	s_lshl_b64 s[66:67], s[28:29], 16
	v_lshl_add_u64 v[82:83], v[106:107], 0, s[66:67]
	global_load_dwordx4 v[70:73], v[82:83], off
	v_lshl_add_u64 v[152:153], v[108:109], 0, s[66:67]
	global_load_dwordx4 v[82:85], v[152:153], off
	v_readfirstlane_b32 s79, v150
	s_and_b64 vcc, exec, s[12:13]
	s_cbranch_vccnz .LBB0_808
	s_and_b64 vcc, exec, s[98:99]
	s_cbranch_vccnz .LBB0_808
	s_add_i32 s28, s75, 0xffffff80
	s_cmp_gt_i32 s28, s73
	s_cbranch_scc1 .LBB0_808
	s_cmp_le_i32 s48, s72
	v_add_u32_e32 v150, s78, v144
	s_mov_b64 s[66:67], -1
	v_add_u32_e32 v152, s78, v145
	v_lshl_add_u32 v153, v142, 2, s71
	s_cbranch_scc0 .LBB0_805
	ds_read_b128 v[34:37], v153 offset:32768
	ds_read_b128 v[38:41], v153 offset:32800
	ds_read_b128 v[42:45], v153 offset:32832
	ds_read_b128 v[46:49], v153 offset:32864
	ds_read_b128 v[50:53], v153 offset:32896
	ds_read_b128 v[54:57], v153 offset:32928
	ds_read_b128 v[58:61], v153 offset:32960
	ds_read_b128 v[62:65], v153 offset:32992
	ds_read_b128 v[154:157], v152
	ds_read_b128 v[158:161], v152 offset:512
	s_waitcnt lgkmcnt(6)
	ds_read_b128 v[210:213], v152 offset:2048
	ds_read_b128 v[214:217], v152 offset:2560
	ds_read_b128 v[218:221], v152 offset:4096
	ds_read_b128 v[222:225], v152 offset:4608
	ds_read_b128 v[226:229], v152 offset:6144
	ds_read_b128 v[230:233], v152 offset:6656
	v_pk_add_f32 v[48:49], v[126:127], v[48:49]
	v_pk_add_f32 v[44:45], v[122:123], v[44:45]
	v_pk_add_f32 v[40:41], v[118:119], v[40:41]
	v_pk_add_f32 v[36:37], v[114:115], v[36:37]
	v_pk_add_f32 v[46:47], v[124:125], v[46:47]
	v_pk_add_f32 v[42:43], v[120:121], v[42:43]
	v_pk_add_f32 v[38:39], v[116:117], v[38:39]
	v_pk_add_f32 v[34:35], v[112:113], v[34:35]
	s_waitcnt lgkmcnt(8)
	v_pk_add_f32 v[64:65], v[126:127], v[64:65]
	v_pk_add_f32 v[60:61], v[122:123], v[60:61]
	s_waitcnt lgkmcnt(7)
	v_mfma_f32_32x32x16_bf16 v[34:49], v[154:157], v[94:97], v[34:49]
	v_add_f32_e64 v56, v118, v56
	v_add_f32_e64 v57, v119, v57
	v_add_f32_e64 v52, v114, v52
	v_add_f32_e64 v53, v115, v53
	v_add_f32_e64 v62, v124, v62
	v_add_f32_e64 v63, v125, v63
	v_pk_add_f32 v[58:59], v[120:121], v[58:59]
	v_pk_add_f32 v[54:55], v[116:117], v[54:55]
	v_pk_add_f32 v[50:51], v[112:113], v[50:51]
	s_waitcnt lgkmcnt(6)
	s_nop 0
	v_mfma_f32_32x32x16_bf16 v[50:65], v[158:161], v[94:97], v[50:65]
	s_waitcnt lgkmcnt(5)
	v_mfma_f32_32x32x16_bf16 v[34:49], v[210:213], v[98:101], v[34:49]
	s_waitcnt lgkmcnt(4)
	v_mfma_f32_32x32x16_bf16 v[50:65], v[214:217], v[98:101], v[50:65]
	s_waitcnt lgkmcnt(3)
	v_mfma_f32_32x32x16_bf16 v[34:49], v[218:221], v[102:105], v[34:49]
	s_waitcnt lgkmcnt(2)
	v_mfma_f32_32x32x16_bf16 v[50:65], v[222:225], v[102:105], v[50:65]
	s_waitcnt lgkmcnt(1)
	v_mfma_f32_32x32x16_bf16 v[34:49], v[226:229], v[90:93], v[34:49]
	s_waitcnt lgkmcnt(0)
	v_mfma_f32_32x32x16_bf16 v[50:65], v[230:233], v[90:93], v[50:65]
	s_nop 9
	v_exp_f32_e32 v34, v34
	v_exp_f32_e32 v35, v35
	v_exp_f32_e32 v36, v36
	v_exp_f32_e32 v37, v37
	v_exp_f32_e32 v38, v38
	v_pk_add_f32 v[154:155], v[34:35], 0 op_sel_hi:[1,0]
	v_exp_f32_e32 v39, v39
	v_exp_f32_e32 v50, v50
	v_exp_f32_e32 v51, v51
	v_exp_f32_e32 v52, v52
	v_exp_f32_e32 v53, v53
	v_exp_f32_e32 v54, v54
	v_pk_add_f32 v[154:155], v[50:51], v[154:155]
	v_exp_f32_e32 v55, v55
	v_pk_add_f32 v[154:155], v[36:37], v[154:155]
	v_exp_f32_e32 v40, v40
	v_exp_f32_e32 v41, v41
	v_pk_add_f32 v[154:155], v[52:53], v[154:155]
	v_exp_f32_e32 v56, v56
	v_exp_f32_e32 v57, v57
	v_pk_add_f32 v[154:155], v[38:39], v[154:155]
	v_exp_f32_e32 v42, v42
	v_exp_f32_e32 v43, v43
	v_pk_add_f32 v[154:155], v[54:55], v[154:155]
	v_exp_f32_e32 v58, v58
	v_exp_f32_e32 v59, v59
	v_pk_add_f32 v[154:155], v[40:41], v[154:155]
	v_exp_f32_e32 v44, v44
	v_exp_f32_e32 v45, v45
	v_pk_add_f32 v[154:155], v[56:57], v[154:155]
	v_exp_f32_e32 v60, v60
	v_exp_f32_e32 v61, v61
	v_pk_add_f32 v[154:155], v[42:43], v[154:155]
	v_exp_f32_e32 v46, v46
	v_exp_f32_e32 v47, v47
	v_cvt_pk_bf16_f32 v164, v50, v51
	ds_read_b64_tr_b16 v[50:51],v150 offset:0
	v_pk_add_f32 v[154:155], v[58:59], v[154:155]
	v_exp_f32_e32 v62, v62
	v_exp_f32_e32 v63, v63
	v_cvt_pk_bf16_f32 v165, v52, v53
	ds_read_b64_tr_b16 v[52:53],v150 offset:512
	v_pk_add_f32 v[154:155], v[44:45], v[154:155]
	v_exp_f32_e32 v48, v48
	v_exp_f32_e32 v49, v49
	v_cvt_pk_bf16_f32 v166, v54, v55
	ds_read_b64_tr_b16 v[54:55],v150 offset:1024
	v_pk_add_f32 v[154:155], v[60:61], v[154:155]
	v_exp_f32_e32 v64, v64
	v_exp_f32_e32 v65, v65
	v_cvt_pk_bf16_f32 v167, v56, v57
	ds_read_b64_tr_b16 v[56:57],v150 offset:1536
	v_pk_add_f32 v[154:155], v[46:47], v[154:155]
	v_cvt_pk_bf16_f32 v168, v58, v59
	ds_read_b64_tr_b16 v[58:59],v150 offset:2048
	v_pk_add_f32 v[154:155], v[62:63], v[154:155]
	v_cvt_pk_bf16_f32 v169, v60, v61
	ds_read_b64_tr_b16 v[60:61],v150 offset:2560
	v_pk_add_f32 v[154:155], v[48:49], v[154:155]
	v_cvt_pk_bf16_f32 v170, v62, v63
	ds_read_b64_tr_b16 v[62:63],v150 offset:3072
	v_pk_add_f32 v[154:155], v[64:65], v[154:155]
	v_cvt_pk_bf16_f32 v171, v64, v65
	ds_read_b64_tr_b16 v[64:65],v150 offset:3584
	s_waitcnt lgkmcnt(0)
	v_add_f32_e32 v154, v154, v155
	v_add_f32_e32 v154, v148, v154
	v_cvt_pk_bf16_f32 v156, v34, v35
	v_cvt_pk_bf16_f32 v157, v36, v37
	v_cvt_pk_bf16_f32 v158, v38, v39
	v_cvt_pk_bf16_f32 v159, v40, v41
	v_cvt_pk_bf16_f32 v160, v42, v43
	v_cvt_pk_bf16_f32 v161, v44, v45
	v_cvt_pk_bf16_f32 v162, v46, v47
	v_cvt_pk_bf16_f32 v163, v48, v49
	v_mfma_f32_32x32x16_bf16 v[2:17], v[156:159], v[50:53], v[2:17]
	ds_read_b64_tr_b16 v[172:173],v150 offset:4096
	ds_read_b64_tr_b16 v[174:175],v150 offset:4608
	ds_read_b64_tr_b16 v[176:177],v150 offset:5120
	ds_read_b64_tr_b16 v[178:179],v150 offset:5632
	ds_read_b64_tr_b16 v[180:181],v150 offset:6144
	ds_read_b64_tr_b16 v[182:183],v150 offset:6656
	ds_read_b64_tr_b16 v[184:185],v150 offset:7168
	s_nop 0
	v_mfma_f32_32x32x16_bf16 v[2:17], v[160:163], v[54:57], v[2:17]
	ds_read_b64_tr_b16 v[186:187],v150 offset:7680
	s_waitcnt lgkmcnt(0)
	v_mfma_f32_32x32x16_bf16 v[2:17], v[164:167], v[58:61], v[2:17]
	v_mfma_f32_32x32x16_bf16 v[2:17], v[168:171], v[62:65], v[2:17]
	v_mfma_f32_32x32x16_bf16 v[18:33], v[156:159], v[172:175], v[18:33]
	s_mov_b64 s[66:67], 0
	v_mfma_f32_32x32x16_bf16 v[18:33], v[160:163], v[176:179], v[18:33]
	v_mfma_f32_32x32x16_bf16 v[18:33], v[164:167], v[180:183], v[18:33]
	v_mfma_f32_32x32x16_bf16 v[18:33], v[168:171], v[184:187], v[18:33]

; #define DPP_SHL(v, n) __builtin_bit_cast(float, __builtin_amdgcn_update_dpp(0, __builtin_bit_cast(int, (v)), 0x100 | (n), 0xF, 0xF, true))
; __device__ __forceinline__ float suffix_incl(float v, int lane) {
;     v += DPP_SHL(v, 1); v += DPP_SHL(v, 2); v += DPP_SHL(v, 4); v += DPP_SHL(v, 8);
;     const float t1 = __builtin_bit_cast(float, __builtin_amdgcn_readlane(__builtin_bit_cast(int, v), 16)), t2 = __builtin_bit_cast(float, __builtin_amdgcn_readlane(__builtin_bit_cast(int, v), 32)),
;                 t3 = __builtin_bit_cast(float, __builtin_amdgcn_readlane(__builtin_bit_cast(int, v), 48));
;     const int row = lane >> 4;
;     const float add = (row == 0) ? (t1 + t2) + t3 : (row == 1) ? t2 + t3 : (row == 2) ? t3 : 0.f;
;     return v + add;
.LBB0_815:
	s_andn2_saveexec_b64 s[68:69], s[68:69]
	v_mov_b32_e32 v152, s80
	v_add_f32_e32 v152, s28, v152
	v_add_f32_e32 v152, s78, v152
	s_or_b64 exec, exec, s[68:69]
	v_add_f32_e32 v151, s79, v151
	v_add_f32_e32 v150, v150, v152
	v_add_f32_e32 v152, v151, v150
	v_sub_f32_e32 v139, v152, v139
	v_mul_f32_e32 v139, 0x3fb8aa3b, v139
	s_max_i32 s28, s48, 6
	ds_write_b32 v0, v139 offset:32768
	s_cmp_lg_u32 s81, 0
	s_cbranch_scc1 .Lmy_zw2_s
	s_waitcnt vmcnt(8)
	s_branch .Lmy_zw2_j

.Lmy_zw2_j:
	s_mov_b32 s81, 1
	ds_write_b128 v149, v[78:81]
	ds_write_b128 v149, v[86:89] offset:8192
	s_add_i32 s28, s28, -6
	s_waitcnt lgkmcnt(0)
	s_lshl_b64 s[68:69], s[28:29], 11
	v_lshl_add_u64 v[78:79], v[110:111], 0, s[68:69]
	global_load_dword v139, v[78:79], off
	s_lshl_b64 s[68:69], s[28:29], 16
	v_lshl_add_u64 v[86:87], v[106:107], 0, s[68:69]
	global_load_dwordx4 v[78:81], v[86:87], off
	v_lshl_add_u64 v[152:153], v[108:109], 0, s[68:69]
	global_load_dwordx4 v[86:89], v[152:153], off
	v_readfirstlane_b32 s70, v150
	s_andn2_b64 vcc, exec, s[60:61]
	s_mov_b64 s[68:69], -1
	s_cbranch_vccnz .LBB0_819
	s_add_i32 s28, s75, 0xffffff40
	s_mov_b64 s[68:69], 0

; __device__ __forceinline__ void attn_unit(const UnitDesc& u, LAS unsigned char* shm, float qkmax, float thresh) {
;     ...
;     asm volatile("s_waitcnt vmcnt(0)" : "+v"(kA), "+v"(vA), "+v"(kB), "+v"(vB), "+v"(kC), "+v"(vC), "+v"(lA), "+v"(lB), "+v"(lC) :: "memory");
;     if (active) {
;         u32x4 zv4[4];
; #pragma unroll
;         for (int i = 0; i < 4; ++i) zv4[i] = *(const u32x4*)(u.Zg + (size_t)(wid * 32 + i * 8 + (lane >> 3)) * 512 + (lane & 7) * 8);
;         { auto rr = __builtin_amdgcn_permlane32_swap(__float_as_uint(l_reg), __float_as_uint(l_reg), false, false); l_reg = __uint_as_float(rr[0]) + __uint_as_float(rr[1]); }
.LBB0_829:
	s_or_b64 exec, exec, s[62:63]
	s_nop 0
	s_and_b64 vcc, exec, s[12:13]
	s_cbranch_vccnz .LBB0_719
	s_nop 7
	s_nop 7
	v_mov_b64_e32 v[34:35], v[2:3]
	v_mov_b64_e32 v[36:37], v[4:5]
	v_mov_b64_e32 v[38:39], v[6:7]
	v_mov_b64_e32 v[40:41], v[8:9]
	v_mov_b64_e32 v[42:43], v[10:11]
	v_mov_b64_e32 v[44:45], v[12:13]
	v_mov_b64_e32 v[46:47], v[14:15]
	v_mov_b64_e32 v[48:49], v[16:17]
	v_mov_b64_e32 v[50:51], v[18:19]
	v_mov_b64_e32 v[52:53], v[20:21]
	v_mov_b64_e32 v[54:55], v[22:23]
	v_mov_b64_e32 v[56:57], v[24:25]
	v_mov_b64_e32 v[58:59], v[26:27]
	v_mov_b64_e32 v[60:61], v[28:29]
	v_mov_b64_e32 v[62:63], v[30:31]
	v_mov_b64_e32 v[64:65], v[32:33]
	s_lshl_b64 s[6:7], s[44:45], 1
	s_add_u32 s8, s24, s6
	v_lshrrev_b32_e32 v20, 3, v137
	s_addc_u32 s9, s25, s7
	s_lshl_b64 s[6:7], s[46:47], 1
	v_or_b32_e32 v18, s49, v20
	s_add_u32 s8, s8, s6
	v_and_b32_e32 v0, 56, v138
	v_or_b32_e32 v6, 8, v18
	s_addc_u32 s9, s9, s7
	v_lshlrev_b32_e32 v0, 1, v0
	v_ashrrev_i32_e32 v19, 31, v18
	v_ashrrev_i32_e32 v7, 31, v6
	v_lshl_add_u64 v[2:3], s[8:9], 0, v[0:1]
	v_lshlrev_b64 v[4:5], 10, v[18:19]
	v_lshlrev_b64 v[6:7], 10, v[6:7]
	v_lshl_add_u64 v[4:5], v[2:3], 0, v[4:5]
	v_lshl_add_u64 v[6:7], v[2:3], 0, v[6:7]
	v_or_b32_e32 v4, 16, v18
	v_or_b32_e32 v6, 24, v18
	v_ashrrev_i32_e32 v5, 31, v4
	v_ashrrev_i32_e32 v7, 31, v6
	v_lshlrev_b64 v[4:5], 10, v[4:5]
	v_lshlrev_b64 v[6:7], 10, v[6:7]
	v_lshl_add_u64 v[4:5], v[2:3], 0, v[4:5]
	v_lshl_add_u64 v[2:3], v[2:3], 0, v[6:7]
	s_nop 0
	s_waitcnt vmcnt(3)
	v_mov_b64_e32 v[14:15], v[198:199]
	v_mov_b64_e32 v[16:17], v[200:201]
	v_mov_b64_e32 v[10:11], v[204:205]
	v_mov_b64_e32 v[12:13], v[206:207]
	v_mov_b64_e32 v[6:7], v[234:235]
	v_mov_b64_e32 v[8:9], v[236:237]
	v_mov_b64_e32 v[2:3], v[248:249]
	v_mov_b64_e32 v[4:5], v[250:251]
	v_mov_b32_e32 v21, v148
	s_lshl_b32 s8, s49, 2
	s_nop 0
	v_permlane32_swap_b32_e32 v148, v21
	s_add_i32 s10, s8, 0
	v_cmp_gt_u32_e32 vcc, 32, v137
	s_and_saveexec_b64 s[8:9], vcc
	s_cbranch_execz .LBB0_718
	v_add_f32_e32 v21, v148, v21
	v_lshl_add_u32 v22, v135, 2, s10
	ds_write_b32 v22, v21 offset:36864
	s_branch .LBB0_718
